# scan: waves 4-7 issue their q_e loads inside the state-update MFMA block
# baseline (speedup 1.0000x reference)
; __device__ __forceinline__ void phase_scan(const Args& a, unsigned char* smem, int tid, int lane, int wave) {
;     ...
;         auto stepf = [&](const int step, unsigned& sc_issue, unsigned& sc_consume) __attribute__((always_inline)) {
;             const int nstep = step < 259 ? step + 1 : step, n2 = step < 258 ? step + 2 : 259;
;             SCAN_LOAD(nstep, nqe, nat);
;             SCAN_GLOAD(n2, gnxt);
;     ...
;             { int ss = step + SCOUT; ss = ss > 259 ? 259 : ss; const int gcs = SCAN_GC(ss); sc_issue = *(const unsigned*)(scb + (size_t)gcs * scsg); }
;     ...
;             const int gc = SCAN_GC(step); const size_t row0 = (size_t)gc * 64;
;             bf16x8 kdA[4];
;             { const bf16_t* kp = KDT + (((size_t)gc * 4 + h) * 8 + kb) * 2048 + lane * 8;
; #pragma unroll
;               for (int q = 0; q < 4; ++q) kdA[q] = *(const bf16x8*)(kp + 512 * q); }
;             const int rbuf = step & 1, nbuf = rbuf ^ 1;
;             if (gc < 512) {
;                 u32x4 s0, s1;
;                 s0.x = pk2(S[0], S[1]); s0.y = pk2(S[2], S[3]); s0.z = pk2(S[4], S[5]); s0.w = pk2(S[6], S[7]);
;                 s1.x = pk2(S[8], S[9]); s1.y = pk2(S[10], S[11]); s1.z = pk2(S[12], S[13]); s1.w = pk2(S[14], S[15]);
;                 const bf16x8 sb0 = __builtin_bit_cast(bf16x8, s0), sb1 = __builtin_bit_cast(bf16x8, s1);
;                 f32x16 o0, o1;
; #pragma unroll
;                 for (int i = 0; i < 16; ++i) { o0[i] = 0.f; o1[i] = 0.f; }
;                 o0 = mfma32(qeA[0], sb0, o0); o0 = mfma32(qeA[1], sb1, o0);
;                 o1 = mfma32(qeA[2], sb0, o1); o1 = mfma32(qeA[3], sb1, o1);
;                 const int w3 = wave & 3;
;                 const bf16x8 vs = w3 == 0 ? vB[0] : (w3 == 1 ? vB[1] : (w3 == 2 ? vB[2] : vB[3]));
;                 if (wave < 4) o0 = mfma32(atA, vs, o0); else o1 = mfma32(atA, vs, o1);
;                 unsigned* rb = red + (size_t)(rbuf * 8 + wave) * 1024 + lane; unsigned* rbx = red + (size_t)(rbuf * 8 + wave) * 1024 + (lane ^ 32);
; #pragma unroll
;                 for (int i = 0; i < 8; ++i) { unsigned* w_ = (i & 1) ? rbx : rb; w_[i * 64] = pk2(o0[2 * i], o0[2 * i + 1]); w_[512 + i * 64] = pk2(o1[2 * i], o1[2 * i + 1]); }
;             }
;             SCAN_GSTORE(nbuf, gcur);
;             __syncthreads();
;             if (gc < 512) {
.Lscan_pathB:
	s_waitcnt vmcnt(10)
	ds_write_b128 v239, v[204:207]
	global_load_dwordx4 v[204:207], v[194:195], off
	v_lshl_add_u64 v[194:195], v[194:195], 0, v[254:255]
	v_cvt_pk_bf16_f32 v48, v0, v1
	v_cvt_pk_bf16_f32 v49, v2, v3
	v_cvt_pk_bf16_f32 v50, v4, v5
	v_cvt_pk_bf16_f32 v51, v6, v7
	v_cvt_pk_bf16_f32 v52, v8, v9
	v_cvt_pk_bf16_f32 v53, v10, v11
	v_cvt_pk_bf16_f32 v54, v12, v13
	v_cvt_pk_bf16_f32 v55, v14, v15
	v_mfma_f32_32x32x16_bf16 v[16:31], v[56:59], v[48:51], 0
	v_pk_mul_f32 v[0:1], v[162:163], v[0:1]
	v_pk_mul_f32 v[2:3], v[164:165], v[2:3]
	v_pk_mul_f32 v[4:5], v[166:167], v[4:5]
	v_mfma_f32_32x32x16_bf16 v[32:47], v[64:67], v[48:51], 0
	v_pk_mul_f32 v[6:7], v[168:169], v[6:7]
	v_pk_mul_f32 v[8:9], v[170:171], v[8:9]
	v_pk_mul_f32 v[10:11], v[172:173], v[10:11]
	v_mfma_f32_32x32x16_bf16 v[16:31], v[60:63], v[52:55], v[16:31]
	v_pk_mul_f32 v[12:13], v[174:175], v[12:13]
	v_pk_mul_f32 v[14:15], v[176:177], v[14:15]
	v_mfma_f32_32x32x16_bf16 v[32:47], v[68:71], v[52:55], v[32:47]
	v_mfma_f32_32x32x16_bf16 v[16:31], v[72:75], v[196:199], v[16:31]
	v_mfma_f32_32x32x16_bf16 v[0:15], v[76:79], v[128:131], v[0:15]
	global_load_dwordx4 v[56:59], v232, s[34:35] offset:-4096
	v_mfma_f32_32x32x16_bf16 v[0:15], v[80:83], v[132:135], v[0:15]
	global_load_dwordx4 v[60:63], v232, s[34:35]
	v_mfma_f32_32x32x16_bf16 v[0:15], v[84:87], v[136:139], v[0:15]
	global_load_dwordx4 v[64:67], v233, s[34:35] offset:-4096
	v_mfma_f32_32x32x16_bf16 v[0:15], v[88:91], v[140:143], v[0:15]
	global_load_dwordx4 v[68:71], v233, s[34:35]
	ds_read_b128 v[144:147], v246 offset:4096
	ds_read_b128 v[148:151], v246 offset:5120
	ds_read_b128 v[152:155], v246 offset:6144
	global_load_dwordx4 v[76:79], v235, s[32:33]
	ds_read_b128 v[156:159], v246 offset:7168
	ds_read_b128 v[200:203], v248 offset:4096
	ds_read_b128 v[178:181], v247 offset:1024
	ds_read_b128 v[182:185], v247 offset:1056
	ds_read_b128 v[186:189], v247 offset:1088
	ds_read_b128 v[190:193], v247 offset:1120
	global_load_dwordx4 v[80:83], v235, s[32:33] offset:1024
	v_cvt_pk_bf16_f32 v16, v16, v17
	v_cvt_pk_bf16_f32 v18, v18, v19
	v_cvt_pk_bf16_f32 v20, v20, v21
	v_cvt_pk_bf16_f32 v22, v22, v23
	v_cvt_pk_bf16_f32 v24, v24, v25
	v_cvt_pk_bf16_f32 v26, v26, v27
	v_cvt_pk_bf16_f32 v28, v28, v29
	global_load_dwordx4 v[84:87], v235, s[32:33] offset:2048
	v_cvt_pk_bf16_f32 v30, v30, v31
	ds_write2st64_b32 v241, v16, v20 offset0:0 offset1:2
	ds_write2st64_b32 v242, v18, v22 offset0:1 offset1:3
	ds_write2st64_b32 v241, v24, v28 offset0:4 offset1:6
	ds_write2st64_b32 v242, v26, v30 offset0:5 offset1:7
	v_cvt_pk_bf16_f32 v32, v32, v33
	v_cvt_pk_bf16_f32 v34, v34, v35
	global_load_dwordx4 v[88:91], v235, s[32:33] offset:3072
	v_cvt_pk_bf16_f32 v36, v36, v37
	v_cvt_pk_bf16_f32 v38, v38, v39
	v_cvt_pk_bf16_f32 v40, v40, v41
	v_cvt_pk_bf16_f32 v42, v42, v43
	v_cvt_pk_bf16_f32 v44, v44, v45
	v_cvt_pk_bf16_f32 v46, v46, v47
	global_load_dwordx4 v[72:75], v251, s[36:37]
	ds_write2st64_b32 v243, v32, v36 offset0:0 offset1:2
	ds_write2st64_b32 v244, v34, v38 offset0:1 offset1:3
	ds_write2st64_b32 v243, v40, v44 offset0:4 offset1:6
	ds_write2st64_b32 v244, v42, v46 offset0:5 offset1:7
	s_add_u32 s32, s32, s53
	s_addc_u32 s33, s33, s56
	s_add_u32 s34, s34, s53
	s_addc_u32 s35, s35, s56
	s_add_u32 s36, s36, s54
	s_addc_u32 s37, s37, s56
	s_waitcnt lgkmcnt(0)
	s_barrier
	s_waitcnt vmcnt(10)
	ds_write_b128 v240, v[208:211]
	global_load_dwordx4 v[208:211], v[194:195], off
	v_lshl_add_u64 v[194:195], v[194:195], 0, v[254:255]
	ds_read2st64_b64 v[212:215], v245 offset0:0 offset1:8
	ds_read2st64_b64 v[216:219], v245 offset0:16 offset1:24
	ds_read2st64_b64 v[220:223], v245 offset0:32 offset1:40
	ds_read2st64_b64 v[224:227], v245 offset0:48 offset1:56
	s_waitcnt lgkmcnt(3)
	v_lshlrev_b32_e32 v229, 16, v213
	v_lshlrev_b32_e32 v228, 16, v212
	v_pk_add_f32 v[228:229], v[228:229], 0 op_sel_hi:[1,0]
	v_and_b32_e32 v231, 0xffff0000, v213
	v_and_b32_e32 v230, 0xffff0000, v212
	v_pk_add_f32 v[230:231], v[230:231], 0 op_sel_hi:[1,0]
	v_lshlrev_b32_e32 v49, 16, v215
	v_lshlrev_b32_e32 v48, 16, v214
	v_pk_add_f32 v[228:229], v[228:229], v[48:49]
	v_and_b32_e32 v215, 0xffff0000, v215
	v_and_b32_e32 v214, 0xffff0000, v214
	v_pk_add_f32 v[230:231], v[230:231], v[214:215]
	s_waitcnt lgkmcnt(2)
	v_lshlrev_b32_e32 v49, 16, v217
	v_lshlrev_b32_e32 v48, 16, v216
	v_pk_add_f32 v[228:229], v[228:229], v[48:49]
	v_and_b32_e32 v217, 0xffff0000, v217
	v_and_b32_e32 v216, 0xffff0000, v216
	v_pk_add_f32 v[230:231], v[230:231], v[216:217]
	v_lshlrev_b32_e32 v49, 16, v219
	v_lshlrev_b32_e32 v48, 16, v218
	v_pk_add_f32 v[228:229], v[228:229], v[48:49]
	v_and_b32_e32 v219, 0xffff0000, v219
	v_and_b32_e32 v218, 0xffff0000, v218
	v_pk_add_f32 v[230:231], v[230:231], v[218:219]
	s_waitcnt lgkmcnt(1)
	v_lshlrev_b32_e32 v49, 16, v221
	v_lshlrev_b32_e32 v48, 16, v220
	v_pk_add_f32 v[228:229], v[228:229], v[48:49]
	v_and_b32_e32 v221, 0xffff0000, v221
	v_and_b32_e32 v220, 0xffff0000, v220
	v_pk_add_f32 v[230:231], v[230:231], v[220:221]
	v_lshlrev_b32_e32 v49, 16, v223
	v_lshlrev_b32_e32 v48, 16, v222
	v_pk_add_f32 v[228:229], v[228:229], v[48:49]
	v_and_b32_e32 v223, 0xffff0000, v223
	v_and_b32_e32 v222, 0xffff0000, v222
	v_pk_add_f32 v[230:231], v[230:231], v[222:223]
	s_waitcnt lgkmcnt(0)
; __device__ __forceinline__ void phase_scan(const Args& a, unsigned char* smem, int tid, int lane, int wave) {
;     ...
;         auto stepf = [&](const int step, unsigned& sc_issue, unsigned& sc_consume) __attribute__((always_inline)) {
;             const int nstep = step < 259 ? step + 1 : step, n2 = step < 258 ? step + 2 : 259;
;             SCAN_LOAD(nstep, nqe, nat);
;             SCAN_GLOAD(n2, gnxt);
;     ...
;             { int ss = step + SCOUT; ss = ss > 259 ? 259 : ss; const int gcs = SCAN_GC(ss); sc_issue = *(const unsigned*)(scb + (size_t)gcs * scsg); }
;     ...
;             const int gc = SCAN_GC(step); const size_t row0 = (size_t)gc * 64;
;             bf16x8 kdA[4];
;             { const bf16_t* kp = KDT + (((size_t)gc * 4 + h) * 8 + kb) * 2048 + lane * 8;
; #pragma unroll
;               for (int q = 0; q < 4; ++q) kdA[q] = *(const bf16x8*)(kp + 512 * q); }
;             const int rbuf = step & 1, nbuf = rbuf ^ 1;
;             if (gc < 512) {
;                 u32x4 s0, s1;
;                 s0.x = pk2(S[0], S[1]); s0.y = pk2(S[2], S[3]); s0.z = pk2(S[4], S[5]); s0.w = pk2(S[6], S[7]);
;                 s1.x = pk2(S[8], S[9]); s1.y = pk2(S[10], S[11]); s1.z = pk2(S[12], S[13]); s1.w = pk2(S[14], S[15]);
;                 const bf16x8 sb0 = __builtin_bit_cast(bf16x8, s0), sb1 = __builtin_bit_cast(bf16x8, s1);
;                 f32x16 o0, o1;
; #pragma unroll
;                 for (int i = 0; i < 16; ++i) { o0[i] = 0.f; o1[i] = 0.f; }
;                 o0 = mfma32(qeA[0], sb0, o0); o0 = mfma32(qeA[1], sb1, o0);
;                 o1 = mfma32(qeA[2], sb0, o1); o1 = mfma32(qeA[3], sb1, o1);
;                 const int w3 = wave & 3;
;                 const bf16x8 vs = w3 == 0 ? vB[0] : (w3 == 1 ? vB[1] : (w3 == 2 ? vB[2] : vB[3]));
;                 if (wave < 4) o0 = mfma32(atA, vs, o0); else o1 = mfma32(atA, vs, o1);
;                 unsigned* rb = red + (size_t)(rbuf * 8 + wave) * 1024 + lane; unsigned* rbx = red + (size_t)(rbuf * 8 + wave) * 1024 + (lane ^ 32);
; #pragma unroll
;                 for (int i = 0; i < 8; ++i) { unsigned* w_ = (i & 1) ? rbx : rb; w_[i * 64] = pk2(o0[2 * i], o0[2 * i + 1]); w_[512 + i * 64] = pk2(o1[2 * i], o1[2 * i + 1]); }
;             }
;             SCAN_GSTORE(nbuf, gcur);
;             __syncthreads();
;             if (gc < 512) {
	v_lshlrev_b32_e32 v49, 16, v225
	v_lshlrev_b32_e32 v48, 16, v224
	v_pk_add_f32 v[228:229], v[228:229], v[48:49]
	v_and_b32_e32 v225, 0xffff0000, v225
	v_and_b32_e32 v224, 0xffff0000, v224
	v_pk_add_f32 v[230:231], v[230:231], v[224:225]
	v_lshlrev_b32_e32 v49, 16, v227
	v_lshlrev_b32_e32 v48, 16, v226
	v_pk_add_f32 v[228:229], v[228:229], v[48:49]
	v_and_b32_e32 v227, 0xffff0000, v227
	v_and_b32_e32 v226, 0xffff0000, v226
	v_pk_add_f32 v[230:231], v[230:231], v[226:227]
	v_cvt_pk_bf16_f32 v228, v228, v229
	v_cvt_pk_bf16_f32 v230, v230, v231
	global_store_dword v249, v228, s[38:39]
	global_store_dword v250, v230, s[38:39]
	s_add_u32 s38, s38, s55
	s_addc_u32 s39, s39, s56
	v_cvt_pk_bf16_f32 v48, v0, v1
	v_cvt_pk_bf16_f32 v49, v2, v3
	v_cvt_pk_bf16_f32 v50, v4, v5
	v_cvt_pk_bf16_f32 v51, v6, v7
	v_cvt_pk_bf16_f32 v52, v8, v9
	v_cvt_pk_bf16_f32 v53, v10, v11
	v_cvt_pk_bf16_f32 v54, v12, v13
	v_cvt_pk_bf16_f32 v55, v14, v15
	v_mfma_f32_32x32x16_bf16 v[16:31], v[92:95], v[48:51], 0
	v_pk_mul_f32 v[0:1], v[178:179], v[0:1]
	v_pk_mul_f32 v[2:3], v[180:181], v[2:3]
	v_pk_mul_f32 v[4:5], v[182:183], v[4:5]
	v_mfma_f32_32x32x16_bf16 v[32:47], v[100:103], v[48:51], 0
	v_pk_mul_f32 v[6:7], v[184:185], v[6:7]
	v_pk_mul_f32 v[8:9], v[186:187], v[8:9]
	v_pk_mul_f32 v[10:11], v[188:189], v[10:11]
	v_mfma_f32_32x32x16_bf16 v[16:31], v[96:99], v[52:55], v[16:31]
	v_pk_mul_f32 v[12:13], v[190:191], v[12:13]
	v_pk_mul_f32 v[14:15], v[192:193], v[14:15]
	v_mfma_f32_32x32x16_bf16 v[32:47], v[104:107], v[52:55], v[32:47]
	v_mfma_f32_32x32x16_bf16 v[16:31], v[108:111], v[200:203], v[16:31]
	v_mfma_f32_32x32x16_bf16 v[0:15], v[112:115], v[144:147], v[0:15]
	global_load_dwordx4 v[92:95], v232, s[34:35] offset:-4096
	v_mfma_f32_32x32x16_bf16 v[0:15], v[116:119], v[148:151], v[0:15]
	global_load_dwordx4 v[96:99], v232, s[34:35]
	v_mfma_f32_32x32x16_bf16 v[0:15], v[120:123], v[152:155], v[0:15]
	global_load_dwordx4 v[100:103], v233, s[34:35] offset:-4096
	v_mfma_f32_32x32x16_bf16 v[0:15], v[124:127], v[156:159], v[0:15]
	global_load_dwordx4 v[104:107], v233, s[34:35]
	ds_read_b128 v[128:131], v246 offset:0
	ds_read_b128 v[132:135], v246 offset:1024
	ds_read_b128 v[136:139], v246 offset:2048
	global_load_dwordx4 v[112:115], v235, s[32:33]
	ds_read_b128 v[140:143], v246 offset:3072
	ds_read_b128 v[196:199], v248 offset:0
	ds_read_b128 v[162:165], v247 offset:0
	ds_read_b128 v[166:169], v247 offset:32
	ds_read_b128 v[170:173], v247 offset:64
	ds_read_b128 v[174:177], v247 offset:96
	global_load_dwordx4 v[116:119], v235, s[32:33] offset:1024
	v_cvt_pk_bf16_f32 v16, v16, v17
	v_cvt_pk_bf16_f32 v18, v18, v19
	v_cvt_pk_bf16_f32 v20, v20, v21
	v_cvt_pk_bf16_f32 v22, v22, v23
	v_cvt_pk_bf16_f32 v24, v24, v25
	v_cvt_pk_bf16_f32 v26, v26, v27
	v_cvt_pk_bf16_f32 v28, v28, v29
	global_load_dwordx4 v[120:123], v235, s[32:33] offset:2048
	v_cvt_pk_bf16_f32 v30, v30, v31
	ds_write2st64_b32 v241, v16, v20 offset0:128 offset1:130
	ds_write2st64_b32 v242, v18, v22 offset0:129 offset1:131
	ds_write2st64_b32 v241, v24, v28 offset0:132 offset1:134
	ds_write2st64_b32 v242, v26, v30 offset0:133 offset1:135
	v_cvt_pk_bf16_f32 v32, v32, v33
	v_cvt_pk_bf16_f32 v34, v34, v35
	global_load_dwordx4 v[124:127], v235, s[32:33] offset:3072
	v_cvt_pk_bf16_f32 v36, v36, v37
	v_cvt_pk_bf16_f32 v38, v38, v39
	v_cvt_pk_bf16_f32 v40, v40, v41
	v_cvt_pk_bf16_f32 v42, v42, v43
	v_cvt_pk_bf16_f32 v44, v44, v45
	v_cvt_pk_bf16_f32 v46, v46, v47
	global_load_dwordx4 v[108:111], v251, s[36:37]
	ds_write2st64_b32 v243, v32, v36 offset0:128 offset1:130
	ds_write2st64_b32 v244, v34, v38 offset0:129 offset1:131
	ds_write2st64_b32 v243, v40, v44 offset0:132 offset1:134
	ds_write2st64_b32 v244, v42, v46 offset0:133 offset1:135
	s_add_u32 s32, s32, s53
	s_addc_u32 s33, s33, s56
	s_add_u32 s34, s34, s53
	s_addc_u32 s35, s35, s56
	s_add_u32 s36, s36, s54
	s_addc_u32 s37, s37, s56
	s_waitcnt lgkmcnt(0)
	s_barrier
	s_waitcnt vmcnt(12)
	ds_write_b128 v239, v[204:207]
	global_load_dwordx4 v[204:207], v[194:195], off
	v_lshl_add_u64 v[194:195], v[194:195], 0, v[254:255]
	ds_read2st64_b64 v[212:215], v245 offset0:64 offset1:72
	ds_read2st64_b64 v[216:219], v245 offset0:80 offset1:88
	ds_read2st64_b64 v[220:223], v245 offset0:96 offset1:104
	ds_read2st64_b64 v[224:227], v245 offset0:112 offset1:120
	s_waitcnt lgkmcnt(3)
	v_lshlrev_b32_e32 v229, 16, v213
	v_lshlrev_b32_e32 v228, 16, v212
	v_pk_add_f32 v[228:229], v[228:229], 0 op_sel_hi:[1,0]
	v_and_b32_e32 v231, 0xffff0000, v213
	v_and_b32_e32 v230, 0xffff0000, v212
	v_pk_add_f32 v[230:231], v[230:231], 0 op_sel_hi:[1,0]
	v_lshlrev_b32_e32 v49, 16, v215
	v_lshlrev_b32_e32 v48, 16, v214
	v_pk_add_f32 v[228:229], v[228:229], v[48:49]
	v_and_b32_e32 v215, 0xffff0000, v215
	v_and_b32_e32 v214, 0xffff0000, v214
	v_pk_add_f32 v[230:231], v[230:231], v[214:215]
	s_waitcnt lgkmcnt(2)
	v_lshlrev_b32_e32 v49, 16, v217
	v_lshlrev_b32_e32 v48, 16, v216
	v_pk_add_f32 v[228:229], v[228:229], v[48:49]
	v_and_b32_e32 v217, 0xffff0000, v217
	v_and_b32_e32 v216, 0xffff0000, v216
	v_pk_add_f32 v[230:231], v[230:231], v[216:217]
	v_lshlrev_b32_e32 v49, 16, v219
	v_lshlrev_b32_e32 v48, 16, v218
	v_pk_add_f32 v[228:229], v[228:229], v[48:49]
	v_and_b32_e32 v219, 0xffff0000, v219
	v_and_b32_e32 v218, 0xffff0000, v218
	v_pk_add_f32 v[230:231], v[230:231], v[218:219]
	s_waitcnt lgkmcnt(1)
	v_lshlrev_b32_e32 v49, 16, v221
	v_lshlrev_b32_e32 v48, 16, v220
	v_pk_add_f32 v[228:229], v[228:229], v[48:49]
	v_and_b32_e32 v221, 0xffff0000, v221
	v_and_b32_e32 v220, 0xffff0000, v220
	v_pk_add_f32 v[230:231], v[230:231], v[220:221]
	v_lshlrev_b32_e32 v49, 16, v223
	v_lshlrev_b32_e32 v48, 16, v222
	v_pk_add_f32 v[228:229], v[228:229], v[48:49]
	v_and_b32_e32 v223, 0xffff0000, v223
	v_and_b32_e32 v222, 0xffff0000, v222
	v_pk_add_f32 v[230:231], v[230:231], v[222:223]
	s_waitcnt lgkmcnt(0)
; __device__ __forceinline__ void phase_scan(const Args& a, unsigned char* smem, int tid, int lane, int wave) {
;     ...
;         auto stepf = [&](const int step, unsigned& sc_issue, unsigned& sc_consume) __attribute__((always_inline)) {
;             const int nstep = step < 259 ? step + 1 : step, n2 = step < 258 ? step + 2 : 259;
;             SCAN_LOAD(nstep, nqe, nat);
;             SCAN_GLOAD(n2, gnxt);
;     ...
;             { int ss = step + SCOUT; ss = ss > 259 ? 259 : ss; const int gcs = SCAN_GC(ss); sc_issue = *(const unsigned*)(scb + (size_t)gcs * scsg); }
;     ...
;             const int gc = SCAN_GC(step); const size_t row0 = (size_t)gc * 64;
;             bf16x8 kdA[4];
;             { const bf16_t* kp = KDT + (((size_t)gc * 4 + h) * 8 + kb) * 2048 + lane * 8;
; #pragma unroll
;               for (int q = 0; q < 4; ++q) kdA[q] = *(const bf16x8*)(kp + 512 * q); }
;             const int rbuf = step & 1, nbuf = rbuf ^ 1;
;             if (gc < 512) {
;                 u32x4 s0, s1;
;                 s0.x = pk2(S[0], S[1]); s0.y = pk2(S[2], S[3]); s0.z = pk2(S[4], S[5]); s0.w = pk2(S[6], S[7]);
;                 s1.x = pk2(S[8], S[9]); s1.y = pk2(S[10], S[11]); s1.z = pk2(S[12], S[13]); s1.w = pk2(S[14], S[15]);
;                 const bf16x8 sb0 = __builtin_bit_cast(bf16x8, s0), sb1 = __builtin_bit_cast(bf16x8, s1);
;                 f32x16 o0, o1;
; #pragma unroll
;                 for (int i = 0; i < 16; ++i) { o0[i] = 0.f; o1[i] = 0.f; }
;                 o0 = mfma32(qeA[0], sb0, o0); o0 = mfma32(qeA[1], sb1, o0);
;                 o1 = mfma32(qeA[2], sb0, o1); o1 = mfma32(qeA[3], sb1, o1);
;                 const int w3 = wave & 3;
;                 const bf16x8 vs = w3 == 0 ? vB[0] : (w3 == 1 ? vB[1] : (w3 == 2 ? vB[2] : vB[3]));
;                 if (wave < 4) o0 = mfma32(atA, vs, o0); else o1 = mfma32(atA, vs, o1);
;                 unsigned* rb = red + (size_t)(rbuf * 8 + wave) * 1024 + lane; unsigned* rbx = red + (size_t)(rbuf * 8 + wave) * 1024 + (lane ^ 32);
; #pragma unroll
;                 for (int i = 0; i < 8; ++i) { unsigned* w_ = (i & 1) ? rbx : rb; w_[i * 64] = pk2(o0[2 * i], o0[2 * i + 1]); w_[512 + i * 64] = pk2(o1[2 * i], o1[2 * i + 1]); }
;             }
;             SCAN_GSTORE(nbuf, gcur);
;             __syncthreads();
;             if (gc < 512) {
	v_lshlrev_b32_e32 v49, 16, v225
	v_lshlrev_b32_e32 v48, 16, v224
	v_pk_add_f32 v[228:229], v[228:229], v[48:49]
	v_and_b32_e32 v225, 0xffff0000, v225
	v_and_b32_e32 v224, 0xffff0000, v224
	v_pk_add_f32 v[230:231], v[230:231], v[224:225]
	v_lshlrev_b32_e32 v49, 16, v227
	v_lshlrev_b32_e32 v48, 16, v226
	v_pk_add_f32 v[228:229], v[228:229], v[48:49]
	v_and_b32_e32 v227, 0xffff0000, v227
	v_and_b32_e32 v226, 0xffff0000, v226
	v_pk_add_f32 v[230:231], v[230:231], v[226:227]
	v_cvt_pk_bf16_f32 v228, v228, v229
	v_cvt_pk_bf16_f32 v230, v230, v231
	global_store_dword v249, v228, s[38:39]
	global_store_dword v250, v230, s[38:39]
	s_add_u32 s38, s38, s55
	s_addc_u32 s39, s39, s56
	v_cvt_pk_bf16_f32 v48, v0, v1
	v_cvt_pk_bf16_f32 v49, v2, v3
	v_cvt_pk_bf16_f32 v50, v4, v5
	v_cvt_pk_bf16_f32 v51, v6, v7
	v_cvt_pk_bf16_f32 v52, v8, v9
	v_cvt_pk_bf16_f32 v53, v10, v11
	v_cvt_pk_bf16_f32 v54, v12, v13
	v_cvt_pk_bf16_f32 v55, v14, v15
	v_mfma_f32_32x32x16_bf16 v[16:31], v[56:59], v[48:51], 0
	v_pk_mul_f32 v[0:1], v[162:163], v[0:1]
	v_pk_mul_f32 v[2:3], v[164:165], v[2:3]
	v_pk_mul_f32 v[4:5], v[166:167], v[4:5]
	v_mfma_f32_32x32x16_bf16 v[32:47], v[64:67], v[48:51], 0
	v_pk_mul_f32 v[6:7], v[168:169], v[6:7]
	v_pk_mul_f32 v[8:9], v[170:171], v[8:9]
	v_pk_mul_f32 v[10:11], v[172:173], v[10:11]
	v_mfma_f32_32x32x16_bf16 v[16:31], v[60:63], v[52:55], v[16:31]
	v_pk_mul_f32 v[12:13], v[174:175], v[12:13]
	v_pk_mul_f32 v[14:15], v[176:177], v[14:15]
	v_mfma_f32_32x32x16_bf16 v[32:47], v[68:71], v[52:55], v[32:47]
	v_mfma_f32_32x32x16_bf16 v[16:31], v[72:75], v[196:199], v[16:31]
	v_mfma_f32_32x32x16_bf16 v[0:15], v[76:79], v[128:131], v[0:15]
	global_load_dwordx4 v[56:59], v232, s[34:35] offset:-4096
	v_mfma_f32_32x32x16_bf16 v[0:15], v[80:83], v[132:135], v[0:15]
	global_load_dwordx4 v[60:63], v232, s[34:35]
	v_mfma_f32_32x32x16_bf16 v[0:15], v[84:87], v[136:139], v[0:15]
	global_load_dwordx4 v[64:67], v233, s[34:35] offset:-4096
	v_mfma_f32_32x32x16_bf16 v[0:15], v[88:91], v[140:143], v[0:15]
	global_load_dwordx4 v[68:71], v233, s[34:35]
	ds_read_b128 v[144:147], v246 offset:4096
	ds_read_b128 v[148:151], v246 offset:5120
	ds_read_b128 v[152:155], v246 offset:6144
	global_load_dwordx4 v[76:79], v235, s[32:33]
	ds_read_b128 v[156:159], v246 offset:7168
	ds_read_b128 v[200:203], v248 offset:4096
	ds_read_b128 v[178:181], v247 offset:1024
	ds_read_b128 v[182:185], v247 offset:1056
	ds_read_b128 v[186:189], v247 offset:1088
	ds_read_b128 v[190:193], v247 offset:1120
	global_load_dwordx4 v[80:83], v235, s[32:33] offset:1024
	v_cvt_pk_bf16_f32 v16, v16, v17
	v_cvt_pk_bf16_f32 v18, v18, v19
	v_cvt_pk_bf16_f32 v20, v20, v21
	v_cvt_pk_bf16_f32 v22, v22, v23
	v_cvt_pk_bf16_f32 v24, v24, v25
	v_cvt_pk_bf16_f32 v26, v26, v27
	v_cvt_pk_bf16_f32 v28, v28, v29
	global_load_dwordx4 v[84:87], v235, s[32:33] offset:2048
	v_cvt_pk_bf16_f32 v30, v30, v31
	ds_write2st64_b32 v241, v16, v20 offset0:0 offset1:2
	ds_write2st64_b32 v242, v18, v22 offset0:1 offset1:3
	ds_write2st64_b32 v241, v24, v28 offset0:4 offset1:6
	ds_write2st64_b32 v242, v26, v30 offset0:5 offset1:7
	v_cvt_pk_bf16_f32 v32, v32, v33
	v_cvt_pk_bf16_f32 v34, v34, v35
	global_load_dwordx4 v[88:91], v235, s[32:33] offset:3072
	v_cvt_pk_bf16_f32 v36, v36, v37
	v_cvt_pk_bf16_f32 v38, v38, v39
	v_cvt_pk_bf16_f32 v40, v40, v41
	v_cvt_pk_bf16_f32 v42, v42, v43
	v_cvt_pk_bf16_f32 v44, v44, v45
	v_cvt_pk_bf16_f32 v46, v46, v47
	global_load_dwordx4 v[72:75], v251, s[36:37]
	ds_write2st64_b32 v243, v32, v36 offset0:0 offset1:2
	ds_write2st64_b32 v244, v34, v38 offset0:1 offset1:3
	ds_write2st64_b32 v243, v40, v44 offset0:4 offset1:6
	ds_write2st64_b32 v244, v42, v46 offset0:5 offset1:7
	s_add_u32 s32, s32, s53
	s_addc_u32 s33, s33, s56
	s_add_u32 s34, s34, s53
	s_addc_u32 s35, s35, s56
	s_add_u32 s36, s36, s54
	s_addc_u32 s37, s37, s56
	s_waitcnt lgkmcnt(0)
	s_barrier
	s_waitcnt vmcnt(12)
	ds_write_b128 v240, v[208:211]
	global_load_dwordx4 v[208:211], v[194:195], off
	v_lshl_add_u64 v[194:195], v[194:195], 0, v[254:255]
	ds_read2st64_b64 v[212:215], v245 offset0:0 offset1:8
	ds_read2st64_b64 v[216:219], v245 offset0:16 offset1:24
	ds_read2st64_b64 v[220:223], v245 offset0:32 offset1:40
	ds_read2st64_b64 v[224:227], v245 offset0:48 offset1:56
	s_waitcnt lgkmcnt(3)
	v_lshlrev_b32_e32 v229, 16, v213
	v_lshlrev_b32_e32 v228, 16, v212
	v_pk_add_f32 v[228:229], v[228:229], 0 op_sel_hi:[1,0]
	v_and_b32_e32 v231, 0xffff0000, v213
	v_and_b32_e32 v230, 0xffff0000, v212
	v_pk_add_f32 v[230:231], v[230:231], 0 op_sel_hi:[1,0]
	v_lshlrev_b32_e32 v49, 16, v215
	v_lshlrev_b32_e32 v48, 16, v214
	v_pk_add_f32 v[228:229], v[228:229], v[48:49]
	v_and_b32_e32 v215, 0xffff0000, v215
	v_and_b32_e32 v214, 0xffff0000, v214
	v_pk_add_f32 v[230:231], v[230:231], v[214:215]
	s_waitcnt lgkmcnt(2)
	v_lshlrev_b32_e32 v49, 16, v217
	v_lshlrev_b32_e32 v48, 16, v216
	v_pk_add_f32 v[228:229], v[228:229], v[48:49]
	v_and_b32_e32 v217, 0xffff0000, v217
	v_and_b32_e32 v216, 0xffff0000, v216
	v_pk_add_f32 v[230:231], v[230:231], v[216:217]
	v_lshlrev_b32_e32 v49, 16, v219
	v_lshlrev_b32_e32 v48, 16, v218
	v_pk_add_f32 v[228:229], v[228:229], v[48:49]
	v_and_b32_e32 v219, 0xffff0000, v219
	v_and_b32_e32 v218, 0xffff0000, v218
	v_pk_add_f32 v[230:231], v[230:231], v[218:219]
	s_waitcnt lgkmcnt(1)
	v_lshlrev_b32_e32 v49, 16, v221
	v_lshlrev_b32_e32 v48, 16, v220
	v_pk_add_f32 v[228:229], v[228:229], v[48:49]
	v_and_b32_e32 v221, 0xffff0000, v221
	v_and_b32_e32 v220, 0xffff0000, v220
	v_pk_add_f32 v[230:231], v[230:231], v[220:221]
	v_lshlrev_b32_e32 v49, 16, v223
	v_lshlrev_b32_e32 v48, 16, v222
	v_pk_add_f32 v[228:229], v[228:229], v[48:49]
	v_and_b32_e32 v223, 0xffff0000, v223
	v_and_b32_e32 v222, 0xffff0000, v222
	v_pk_add_f32 v[230:231], v[230:231], v[222:223]
	s_waitcnt lgkmcnt(0)
; __device__ __forceinline__ void phase_scan(const Args& a, unsigned char* smem, int tid, int lane, int wave) {
;     ...
;         auto stepf = [&](const int step, unsigned& sc_issue, unsigned& sc_consume) __attribute__((always_inline)) {
;             const int nstep = step < 259 ? step + 1 : step, n2 = step < 258 ? step + 2 : 259;
;             SCAN_LOAD(nstep, nqe, nat);
;             SCAN_GLOAD(n2, gnxt);
;     ...
;             { int ss = step + SCOUT; ss = ss > 259 ? 259 : ss; const int gcs = SCAN_GC(ss); sc_issue = *(const unsigned*)(scb + (size_t)gcs * scsg); }
;     ...
;             const int gc = SCAN_GC(step); const size_t row0 = (size_t)gc * 64;
;             bf16x8 kdA[4];
;             { const bf16_t* kp = KDT + (((size_t)gc * 4 + h) * 8 + kb) * 2048 + lane * 8;
; #pragma unroll
;               for (int q = 0; q < 4; ++q) kdA[q] = *(const bf16x8*)(kp + 512 * q); }
;             const int rbuf = step & 1, nbuf = rbuf ^ 1;
;             if (gc < 512) {
;                 u32x4 s0, s1;
;                 s0.x = pk2(S[0], S[1]); s0.y = pk2(S[2], S[3]); s0.z = pk2(S[4], S[5]); s0.w = pk2(S[6], S[7]);
;                 s1.x = pk2(S[8], S[9]); s1.y = pk2(S[10], S[11]); s1.z = pk2(S[12], S[13]); s1.w = pk2(S[14], S[15]);
;                 const bf16x8 sb0 = __builtin_bit_cast(bf16x8, s0), sb1 = __builtin_bit_cast(bf16x8, s1);
;                 f32x16 o0, o1;
; #pragma unroll
;                 for (int i = 0; i < 16; ++i) { o0[i] = 0.f; o1[i] = 0.f; }
;                 o0 = mfma32(qeA[0], sb0, o0); o0 = mfma32(qeA[1], sb1, o0);
;                 o1 = mfma32(qeA[2], sb0, o1); o1 = mfma32(qeA[3], sb1, o1);
;                 const int w3 = wave & 3;
;                 const bf16x8 vs = w3 == 0 ? vB[0] : (w3 == 1 ? vB[1] : (w3 == 2 ? vB[2] : vB[3]));
;                 if (wave < 4) o0 = mfma32(atA, vs, o0); else o1 = mfma32(atA, vs, o1);
;                 unsigned* rb = red + (size_t)(rbuf * 8 + wave) * 1024 + lane; unsigned* rbx = red + (size_t)(rbuf * 8 + wave) * 1024 + (lane ^ 32);
; #pragma unroll
;                 for (int i = 0; i < 8; ++i) { unsigned* w_ = (i & 1) ? rbx : rb; w_[i * 64] = pk2(o0[2 * i], o0[2 * i + 1]); w_[512 + i * 64] = pk2(o1[2 * i], o1[2 * i + 1]); }
;             }
;             SCAN_GSTORE(nbuf, gcur);
;             __syncthreads();
;             if (gc < 512) {
	v_lshlrev_b32_e32 v49, 16, v225
	v_lshlrev_b32_e32 v48, 16, v224
	v_pk_add_f32 v[228:229], v[228:229], v[48:49]
	v_and_b32_e32 v225, 0xffff0000, v225
	v_and_b32_e32 v224, 0xffff0000, v224
	v_pk_add_f32 v[230:231], v[230:231], v[224:225]
	v_lshlrev_b32_e32 v49, 16, v227
	v_lshlrev_b32_e32 v48, 16, v226
	v_pk_add_f32 v[228:229], v[228:229], v[48:49]
	v_and_b32_e32 v227, 0xffff0000, v227
	v_and_b32_e32 v226, 0xffff0000, v226
	v_pk_add_f32 v[230:231], v[230:231], v[226:227]
	v_cvt_pk_bf16_f32 v228, v228, v229
	v_cvt_pk_bf16_f32 v230, v230, v231
	global_store_dword v249, v228, s[38:39]
	global_store_dword v250, v230, s[38:39]
	s_add_u32 s38, s38, s55
	s_addc_u32 s39, s39, s56
	v_cvt_pk_bf16_f32 v48, v0, v1
	v_cvt_pk_bf16_f32 v49, v2, v3
	v_cvt_pk_bf16_f32 v50, v4, v5
	v_cvt_pk_bf16_f32 v51, v6, v7
	v_cvt_pk_bf16_f32 v52, v8, v9
	v_cvt_pk_bf16_f32 v53, v10, v11
	v_cvt_pk_bf16_f32 v54, v12, v13
	v_cvt_pk_bf16_f32 v55, v14, v15
	v_mfma_f32_32x32x16_bf16 v[16:31], v[92:95], v[48:51], 0
	v_pk_mul_f32 v[0:1], v[178:179], v[0:1]
	v_pk_mul_f32 v[2:3], v[180:181], v[2:3]
	v_pk_mul_f32 v[4:5], v[182:183], v[4:5]
	v_mfma_f32_32x32x16_bf16 v[32:47], v[100:103], v[48:51], 0
	v_pk_mul_f32 v[6:7], v[184:185], v[6:7]
	v_pk_mul_f32 v[8:9], v[186:187], v[8:9]
	v_pk_mul_f32 v[10:11], v[188:189], v[10:11]
	v_mfma_f32_32x32x16_bf16 v[16:31], v[96:99], v[52:55], v[16:31]
	v_pk_mul_f32 v[12:13], v[190:191], v[12:13]
	v_pk_mul_f32 v[14:15], v[192:193], v[14:15]
	v_mfma_f32_32x32x16_bf16 v[32:47], v[104:107], v[52:55], v[32:47]
	v_mfma_f32_32x32x16_bf16 v[16:31], v[108:111], v[200:203], v[16:31]
	v_mfma_f32_32x32x16_bf16 v[0:15], v[112:115], v[144:147], v[0:15]
	global_load_dwordx4 v[92:95], v232, s[34:35] offset:-4096
	v_mfma_f32_32x32x16_bf16 v[0:15], v[116:119], v[148:151], v[0:15]
	global_load_dwordx4 v[96:99], v232, s[34:35]
	v_mfma_f32_32x32x16_bf16 v[0:15], v[120:123], v[152:155], v[0:15]
	global_load_dwordx4 v[100:103], v233, s[34:35] offset:-4096
	v_mfma_f32_32x32x16_bf16 v[0:15], v[124:127], v[156:159], v[0:15]
	global_load_dwordx4 v[104:107], v233, s[34:35]
	ds_read_b128 v[128:131], v246 offset:0
	ds_read_b128 v[132:135], v246 offset:1024
	ds_read_b128 v[136:139], v246 offset:2048
	global_load_dwordx4 v[112:115], v235, s[32:33]
	ds_read_b128 v[140:143], v246 offset:3072
	ds_read_b128 v[196:199], v248 offset:0
	ds_read_b128 v[162:165], v247 offset:0
	ds_read_b128 v[166:169], v247 offset:32
	ds_read_b128 v[170:173], v247 offset:64
	ds_read_b128 v[174:177], v247 offset:96
	global_load_dwordx4 v[116:119], v235, s[32:33] offset:1024
	v_cvt_pk_bf16_f32 v16, v16, v17
	v_cvt_pk_bf16_f32 v18, v18, v19
	v_cvt_pk_bf16_f32 v20, v20, v21
	v_cvt_pk_bf16_f32 v22, v22, v23
	v_cvt_pk_bf16_f32 v24, v24, v25
	v_cvt_pk_bf16_f32 v26, v26, v27
	v_cvt_pk_bf16_f32 v28, v28, v29
	global_load_dwordx4 v[120:123], v235, s[32:33] offset:2048
	v_cvt_pk_bf16_f32 v30, v30, v31
	ds_write2st64_b32 v241, v16, v20 offset0:128 offset1:130
	ds_write2st64_b32 v242, v18, v22 offset0:129 offset1:131
	ds_write2st64_b32 v241, v24, v28 offset0:132 offset1:134
	ds_write2st64_b32 v242, v26, v30 offset0:133 offset1:135
	v_cvt_pk_bf16_f32 v32, v32, v33
	v_cvt_pk_bf16_f32 v34, v34, v35
	global_load_dwordx4 v[124:127], v235, s[32:33] offset:3072
	v_cvt_pk_bf16_f32 v36, v36, v37
	v_cvt_pk_bf16_f32 v38, v38, v39
	v_cvt_pk_bf16_f32 v40, v40, v41
	v_cvt_pk_bf16_f32 v42, v42, v43
	v_cvt_pk_bf16_f32 v44, v44, v45
	v_cvt_pk_bf16_f32 v46, v46, v47
	global_load_dwordx4 v[108:111], v251, s[36:37]
	ds_write2st64_b32 v243, v32, v36 offset0:128 offset1:130
	ds_write2st64_b32 v244, v34, v38 offset0:129 offset1:131
	ds_write2st64_b32 v243, v40, v44 offset0:132 offset1:134
	ds_write2st64_b32 v244, v42, v46 offset0:133 offset1:135
	s_add_u32 s32, s32, s53
	s_addc_u32 s33, s33, s56
	s_add_u32 s34, s34, s53
	s_addc_u32 s35, s35, s56
	s_add_u32 s36, s36, s54
	s_addc_u32 s37, s37, s56
	s_waitcnt lgkmcnt(0)
	s_barrier
	s_mov_b32 s30, 4
.Lscan_loopB:
	s_waitcnt vmcnt(12)
	ds_write_b128 v239, v[204:207]
	global_load_dwordx4 v[204:207], v[194:195], off
	v_lshl_add_u64 v[194:195], v[194:195], 0, v[254:255]
	ds_read2st64_b64 v[212:215], v245 offset0:64 offset1:72
	ds_read2st64_b64 v[216:219], v245 offset0:80 offset1:88
	ds_read2st64_b64 v[220:223], v245 offset0:96 offset1:104
	ds_read2st64_b64 v[224:227], v245 offset0:112 offset1:120
	s_waitcnt lgkmcnt(3)
	v_lshlrev_b32_e32 v229, 16, v213
	v_lshlrev_b32_e32 v228, 16, v212
	v_pk_add_f32 v[228:229], v[228:229], 0 op_sel_hi:[1,0]
	v_and_b32_e32 v231, 0xffff0000, v213
	v_and_b32_e32 v230, 0xffff0000, v212
	v_pk_add_f32 v[230:231], v[230:231], 0 op_sel_hi:[1,0]
	v_lshlrev_b32_e32 v49, 16, v215
	v_lshlrev_b32_e32 v48, 16, v214
	v_pk_add_f32 v[228:229], v[228:229], v[48:49]
	v_and_b32_e32 v215, 0xffff0000, v215
	v_and_b32_e32 v214, 0xffff0000, v214
	v_pk_add_f32 v[230:231], v[230:231], v[214:215]
	s_waitcnt lgkmcnt(2)
	v_lshlrev_b32_e32 v49, 16, v217
	v_lshlrev_b32_e32 v48, 16, v216
	v_pk_add_f32 v[228:229], v[228:229], v[48:49]
	v_and_b32_e32 v217, 0xffff0000, v217
	v_and_b32_e32 v216, 0xffff0000, v216
	v_pk_add_f32 v[230:231], v[230:231], v[216:217]
	v_lshlrev_b32_e32 v49, 16, v219
	v_lshlrev_b32_e32 v48, 16, v218
	v_pk_add_f32 v[228:229], v[228:229], v[48:49]
	v_and_b32_e32 v219, 0xffff0000, v219
	v_and_b32_e32 v218, 0xffff0000, v218
	v_pk_add_f32 v[230:231], v[230:231], v[218:219]
	s_waitcnt lgkmcnt(1)
	v_lshlrev_b32_e32 v49, 16, v221
	v_lshlrev_b32_e32 v48, 16, v220
	v_pk_add_f32 v[228:229], v[228:229], v[48:49]
	v_and_b32_e32 v221, 0xffff0000, v221
	v_and_b32_e32 v220, 0xffff0000, v220
	v_pk_add_f32 v[230:231], v[230:231], v[220:221]
	v_lshlrev_b32_e32 v49, 16, v223
	v_lshlrev_b32_e32 v48, 16, v222
	v_pk_add_f32 v[228:229], v[228:229], v[48:49]
	v_and_b32_e32 v223, 0xffff0000, v223
	v_and_b32_e32 v222, 0xffff0000, v222
	v_pk_add_f32 v[230:231], v[230:231], v[222:223]
	s_waitcnt lgkmcnt(0)
; __device__ __forceinline__ void phase_scan(const Args& a, unsigned char* smem, int tid, int lane, int wave) {
;     ...
;         auto stepf = [&](const int step, unsigned& sc_issue, unsigned& sc_consume) __attribute__((always_inline)) {
;             const int nstep = step < 259 ? step + 1 : step, n2 = step < 258 ? step + 2 : 259;
;             SCAN_LOAD(nstep, nqe, nat);
;             SCAN_GLOAD(n2, gnxt);
;     ...
;             { int ss = step + SCOUT; ss = ss > 259 ? 259 : ss; const int gcs = SCAN_GC(ss); sc_issue = *(const unsigned*)(scb + (size_t)gcs * scsg); }
;     ...
;             const int gc = SCAN_GC(step); const size_t row0 = (size_t)gc * 64;
;             bf16x8 kdA[4];
;             { const bf16_t* kp = KDT + (((size_t)gc * 4 + h) * 8 + kb) * 2048 + lane * 8;
; #pragma unroll
;               for (int q = 0; q < 4; ++q) kdA[q] = *(const bf16x8*)(kp + 512 * q); }
;             const int rbuf = step & 1, nbuf = rbuf ^ 1;
;             if (gc < 512) {
;                 u32x4 s0, s1;
;                 s0.x = pk2(S[0], S[1]); s0.y = pk2(S[2], S[3]); s0.z = pk2(S[4], S[5]); s0.w = pk2(S[6], S[7]);
;                 s1.x = pk2(S[8], S[9]); s1.y = pk2(S[10], S[11]); s1.z = pk2(S[12], S[13]); s1.w = pk2(S[14], S[15]);
;                 const bf16x8 sb0 = __builtin_bit_cast(bf16x8, s0), sb1 = __builtin_bit_cast(bf16x8, s1);
;                 f32x16 o0, o1;
; #pragma unroll
;                 for (int i = 0; i < 16; ++i) { o0[i] = 0.f; o1[i] = 0.f; }
;                 o0 = mfma32(qeA[0], sb0, o0); o0 = mfma32(qeA[1], sb1, o0);
;                 o1 = mfma32(qeA[2], sb0, o1); o1 = mfma32(qeA[3], sb1, o1);
;                 const int w3 = wave & 3;
;                 const bf16x8 vs = w3 == 0 ? vB[0] : (w3 == 1 ? vB[1] : (w3 == 2 ? vB[2] : vB[3]));
;                 if (wave < 4) o0 = mfma32(atA, vs, o0); else o1 = mfma32(atA, vs, o1);
;                 unsigned* rb = red + (size_t)(rbuf * 8 + wave) * 1024 + lane; unsigned* rbx = red + (size_t)(rbuf * 8 + wave) * 1024 + (lane ^ 32);
; #pragma unroll
;                 for (int i = 0; i < 8; ++i) { unsigned* w_ = (i & 1) ? rbx : rb; w_[i * 64] = pk2(o0[2 * i], o0[2 * i + 1]); w_[512 + i * 64] = pk2(o1[2 * i], o1[2 * i + 1]); }
;             }
;             SCAN_GSTORE(nbuf, gcur);
;             __syncthreads();
;             if (gc < 512) {
	v_lshlrev_b32_e32 v49, 16, v225
	v_lshlrev_b32_e32 v48, 16, v224
	v_pk_add_f32 v[228:229], v[228:229], v[48:49]
	v_and_b32_e32 v225, 0xffff0000, v225
	v_and_b32_e32 v224, 0xffff0000, v224
	v_pk_add_f32 v[230:231], v[230:231], v[224:225]
	v_lshlrev_b32_e32 v49, 16, v227
	v_lshlrev_b32_e32 v48, 16, v226
	v_pk_add_f32 v[228:229], v[228:229], v[48:49]
	v_and_b32_e32 v227, 0xffff0000, v227
	v_and_b32_e32 v226, 0xffff0000, v226
	v_pk_add_f32 v[230:231], v[230:231], v[226:227]
	v_cvt_pk_bf16_f32 v228, v228, v229
	v_cvt_pk_bf16_f32 v230, v230, v231
	global_store_dword v249, v228, s[38:39]
	global_store_dword v250, v230, s[38:39]
	s_add_u32 s38, s38, s55
	s_addc_u32 s39, s39, s56
	v_cvt_pk_bf16_f32 v48, v0, v1
	v_cvt_pk_bf16_f32 v49, v2, v3
	v_cvt_pk_bf16_f32 v50, v4, v5
	v_cvt_pk_bf16_f32 v51, v6, v7
	v_cvt_pk_bf16_f32 v52, v8, v9
	v_cvt_pk_bf16_f32 v53, v10, v11
	v_cvt_pk_bf16_f32 v54, v12, v13
	v_cvt_pk_bf16_f32 v55, v14, v15
	v_mfma_f32_32x32x16_bf16 v[16:31], v[56:59], v[48:51], 0
	v_pk_mul_f32 v[0:1], v[162:163], v[0:1]
	v_pk_mul_f32 v[2:3], v[164:165], v[2:3]
	v_pk_mul_f32 v[4:5], v[166:167], v[4:5]
	v_mfma_f32_32x32x16_bf16 v[32:47], v[64:67], v[48:51], 0
	v_pk_mul_f32 v[6:7], v[168:169], v[6:7]
	v_pk_mul_f32 v[8:9], v[170:171], v[8:9]
	v_pk_mul_f32 v[10:11], v[172:173], v[10:11]
	v_mfma_f32_32x32x16_bf16 v[16:31], v[60:63], v[52:55], v[16:31]
	v_pk_mul_f32 v[12:13], v[174:175], v[12:13]
	v_pk_mul_f32 v[14:15], v[176:177], v[14:15]
	v_mfma_f32_32x32x16_bf16 v[32:47], v[68:71], v[52:55], v[32:47]
	v_mfma_f32_32x32x16_bf16 v[16:31], v[72:75], v[196:199], v[16:31]
	v_mfma_f32_32x32x16_bf16 v[0:15], v[76:79], v[128:131], v[0:15]
	global_load_dwordx4 v[56:59], v232, s[34:35] offset:-4096
	v_mfma_f32_32x32x16_bf16 v[0:15], v[80:83], v[132:135], v[0:15]
	global_load_dwordx4 v[60:63], v232, s[34:35]
	v_mfma_f32_32x32x16_bf16 v[0:15], v[84:87], v[136:139], v[0:15]
	global_load_dwordx4 v[64:67], v233, s[34:35] offset:-4096
	v_mfma_f32_32x32x16_bf16 v[0:15], v[88:91], v[140:143], v[0:15]
	global_load_dwordx4 v[68:71], v233, s[34:35]
	ds_read_b128 v[144:147], v246 offset:4096
	ds_read_b128 v[148:151], v246 offset:5120
	ds_read_b128 v[152:155], v246 offset:6144
	global_load_dwordx4 v[76:79], v235, s[32:33]
	ds_read_b128 v[156:159], v246 offset:7168
	ds_read_b128 v[200:203], v248 offset:4096
	ds_read_b128 v[178:181], v247 offset:1024
	ds_read_b128 v[182:185], v247 offset:1056
	ds_read_b128 v[186:189], v247 offset:1088
	ds_read_b128 v[190:193], v247 offset:1120
	global_load_dwordx4 v[80:83], v235, s[32:33] offset:1024
	v_cvt_pk_bf16_f32 v16, v16, v17
	v_cvt_pk_bf16_f32 v18, v18, v19
	v_cvt_pk_bf16_f32 v20, v20, v21
	v_cvt_pk_bf16_f32 v22, v22, v23
	v_cvt_pk_bf16_f32 v24, v24, v25
	v_cvt_pk_bf16_f32 v26, v26, v27
	v_cvt_pk_bf16_f32 v28, v28, v29
	global_load_dwordx4 v[84:87], v235, s[32:33] offset:2048
	v_cvt_pk_bf16_f32 v30, v30, v31
	ds_write2st64_b32 v241, v16, v20 offset0:0 offset1:2
	ds_write2st64_b32 v242, v18, v22 offset0:1 offset1:3
	ds_write2st64_b32 v241, v24, v28 offset0:4 offset1:6
	ds_write2st64_b32 v242, v26, v30 offset0:5 offset1:7
	v_cvt_pk_bf16_f32 v32, v32, v33
	v_cvt_pk_bf16_f32 v34, v34, v35
	global_load_dwordx4 v[88:91], v235, s[32:33] offset:3072
	v_cvt_pk_bf16_f32 v36, v36, v37
	v_cvt_pk_bf16_f32 v38, v38, v39
	v_cvt_pk_bf16_f32 v40, v40, v41
	v_cvt_pk_bf16_f32 v42, v42, v43
	v_cvt_pk_bf16_f32 v44, v44, v45
	v_cvt_pk_bf16_f32 v46, v46, v47
	global_load_dwordx4 v[72:75], v251, s[36:37]
	ds_write2st64_b32 v243, v32, v36 offset0:0 offset1:2
	ds_write2st64_b32 v244, v34, v38 offset0:1 offset1:3
	ds_write2st64_b32 v243, v40, v44 offset0:4 offset1:6
	ds_write2st64_b32 v244, v42, v46 offset0:5 offset1:7
	s_add_u32 s32, s32, s53
	s_addc_u32 s33, s33, s56
	s_add_u32 s34, s34, s53
	s_addc_u32 s35, s35, s56
	s_add_u32 s36, s36, s54
	s_addc_u32 s37, s37, s56
	s_waitcnt lgkmcnt(0)
	s_barrier
; __device__ __forceinline__ void phase_scan(const Args& a, unsigned char* smem, int tid, int lane, int wave) {
;     ...
;         auto stepf = [&](const int step, unsigned& sc_issue, unsigned& sc_consume) __attribute__((always_inline)) {
;             const int nstep = step < 259 ? step + 1 : step, n2 = step < 258 ? step + 2 : 259;
;             SCAN_LOAD(nstep, nqe, nat);
;             SCAN_GLOAD(n2, gnxt);
;     ...
;             { int ss = step + SCOUT; ss = ss > 259 ? 259 : ss; const int gcs = SCAN_GC(ss); sc_issue = *(const unsigned*)(scb + (size_t)gcs * scsg); }
;     ...
;             const int gc = SCAN_GC(step); const size_t row0 = (size_t)gc * 64;
;             bf16x8 kdA[4];
;             { const bf16_t* kp = KDT + (((size_t)gc * 4 + h) * 8 + kb) * 2048 + lane * 8;
; #pragma unroll
;               for (int q = 0; q < 4; ++q) kdA[q] = *(const bf16x8*)(kp + 512 * q); }
;             const int rbuf = step & 1, nbuf = rbuf ^ 1;
;             if (gc < 512) {
;                 u32x4 s0, s1;
;                 s0.x = pk2(S[0], S[1]); s0.y = pk2(S[2], S[3]); s0.z = pk2(S[4], S[5]); s0.w = pk2(S[6], S[7]);
;                 s1.x = pk2(S[8], S[9]); s1.y = pk2(S[10], S[11]); s1.z = pk2(S[12], S[13]); s1.w = pk2(S[14], S[15]);
;                 const bf16x8 sb0 = __builtin_bit_cast(bf16x8, s0), sb1 = __builtin_bit_cast(bf16x8, s1);
;                 f32x16 o0, o1;
; #pragma unroll
;                 for (int i = 0; i < 16; ++i) { o0[i] = 0.f; o1[i] = 0.f; }
;                 o0 = mfma32(qeA[0], sb0, o0); o0 = mfma32(qeA[1], sb1, o0);
;                 o1 = mfma32(qeA[2], sb0, o1); o1 = mfma32(qeA[3], sb1, o1);
;                 const int w3 = wave & 3;
;                 const bf16x8 vs = w3 == 0 ? vB[0] : (w3 == 1 ? vB[1] : (w3 == 2 ? vB[2] : vB[3]));
;                 if (wave < 4) o0 = mfma32(atA, vs, o0); else o1 = mfma32(atA, vs, o1);
;                 unsigned* rb = red + (size_t)(rbuf * 8 + wave) * 1024 + lane; unsigned* rbx = red + (size_t)(rbuf * 8 + wave) * 1024 + (lane ^ 32);
; #pragma unroll
;                 for (int i = 0; i < 8; ++i) { unsigned* w_ = (i & 1) ? rbx : rb; w_[i * 64] = pk2(o0[2 * i], o0[2 * i + 1]); w_[512 + i * 64] = pk2(o1[2 * i], o1[2 * i + 1]); }
;             }
;             SCAN_GSTORE(nbuf, gcur);
;             __syncthreads();
;             if (gc < 512) {
	s_waitcnt vmcnt(12)
	ds_write_b128 v240, v[208:211]
	global_load_dwordx4 v[208:211], v[194:195], off
	v_lshl_add_u64 v[194:195], v[194:195], 0, v[254:255]
	ds_read2st64_b64 v[212:215], v245 offset0:0 offset1:8
	ds_read2st64_b64 v[216:219], v245 offset0:16 offset1:24
	ds_read2st64_b64 v[220:223], v245 offset0:32 offset1:40
	ds_read2st64_b64 v[224:227], v245 offset0:48 offset1:56
	s_waitcnt lgkmcnt(3)
	v_lshlrev_b32_e32 v229, 16, v213
	v_lshlrev_b32_e32 v228, 16, v212
	v_pk_add_f32 v[228:229], v[228:229], 0 op_sel_hi:[1,0]
	v_and_b32_e32 v231, 0xffff0000, v213
	v_and_b32_e32 v230, 0xffff0000, v212
	v_pk_add_f32 v[230:231], v[230:231], 0 op_sel_hi:[1,0]
	v_lshlrev_b32_e32 v49, 16, v215
	v_lshlrev_b32_e32 v48, 16, v214
	v_pk_add_f32 v[228:229], v[228:229], v[48:49]
	v_and_b32_e32 v215, 0xffff0000, v215
	v_and_b32_e32 v214, 0xffff0000, v214
	v_pk_add_f32 v[230:231], v[230:231], v[214:215]
	s_waitcnt lgkmcnt(2)
	v_lshlrev_b32_e32 v49, 16, v217
	v_lshlrev_b32_e32 v48, 16, v216
	v_pk_add_f32 v[228:229], v[228:229], v[48:49]
	v_and_b32_e32 v217, 0xffff0000, v217
	v_and_b32_e32 v216, 0xffff0000, v216
	v_pk_add_f32 v[230:231], v[230:231], v[216:217]
	v_lshlrev_b32_e32 v49, 16, v219
	v_lshlrev_b32_e32 v48, 16, v218
	v_pk_add_f32 v[228:229], v[228:229], v[48:49]
	v_and_b32_e32 v219, 0xffff0000, v219
	v_and_b32_e32 v218, 0xffff0000, v218
	v_pk_add_f32 v[230:231], v[230:231], v[218:219]
	s_waitcnt lgkmcnt(1)
	v_lshlrev_b32_e32 v49, 16, v221
	v_lshlrev_b32_e32 v48, 16, v220
	v_pk_add_f32 v[228:229], v[228:229], v[48:49]
	v_and_b32_e32 v221, 0xffff0000, v221
	v_and_b32_e32 v220, 0xffff0000, v220
	v_pk_add_f32 v[230:231], v[230:231], v[220:221]
	v_lshlrev_b32_e32 v49, 16, v223
	v_lshlrev_b32_e32 v48, 16, v222
	v_pk_add_f32 v[228:229], v[228:229], v[48:49]
	v_and_b32_e32 v223, 0xffff0000, v223
	v_and_b32_e32 v222, 0xffff0000, v222
	v_pk_add_f32 v[230:231], v[230:231], v[222:223]
	s_waitcnt lgkmcnt(0)
	v_lshlrev_b32_e32 v49, 16, v225
	v_lshlrev_b32_e32 v48, 16, v224
	v_pk_add_f32 v[228:229], v[228:229], v[48:49]
	v_and_b32_e32 v225, 0xffff0000, v225
	v_and_b32_e32 v224, 0xffff0000, v224
	v_pk_add_f32 v[230:231], v[230:231], v[224:225]
	v_lshlrev_b32_e32 v49, 16, v227
	v_lshlrev_b32_e32 v48, 16, v226
	v_pk_add_f32 v[228:229], v[228:229], v[48:49]
	v_and_b32_e32 v227, 0xffff0000, v227
	v_and_b32_e32 v226, 0xffff0000, v226
	v_pk_add_f32 v[230:231], v[230:231], v[226:227]
	v_cvt_pk_bf16_f32 v228, v228, v229
	v_cvt_pk_bf16_f32 v230, v230, v231
	global_store_dword v249, v228, s[38:39]
	global_store_dword v250, v230, s[38:39]
	s_add_u32 s38, s38, s55
	s_addc_u32 s39, s39, s56
	v_cvt_pk_bf16_f32 v48, v0, v1
	v_cvt_pk_bf16_f32 v49, v2, v3
	v_cvt_pk_bf16_f32 v50, v4, v5
	v_cvt_pk_bf16_f32 v51, v6, v7
	v_cvt_pk_bf16_f32 v52, v8, v9
	v_cvt_pk_bf16_f32 v53, v10, v11
	v_cvt_pk_bf16_f32 v54, v12, v13
	v_cvt_pk_bf16_f32 v55, v14, v15
	v_mfma_f32_32x32x16_bf16 v[16:31], v[92:95], v[48:51], 0
	v_pk_mul_f32 v[0:1], v[178:179], v[0:1]
	v_pk_mul_f32 v[2:3], v[180:181], v[2:3]
	v_pk_mul_f32 v[4:5], v[182:183], v[4:5]
	v_mfma_f32_32x32x16_bf16 v[32:47], v[100:103], v[48:51], 0
	v_pk_mul_f32 v[6:7], v[184:185], v[6:7]
	v_pk_mul_f32 v[8:9], v[186:187], v[8:9]
	v_pk_mul_f32 v[10:11], v[188:189], v[10:11]
	v_mfma_f32_32x32x16_bf16 v[16:31], v[96:99], v[52:55], v[16:31]
	v_pk_mul_f32 v[12:13], v[190:191], v[12:13]
	v_pk_mul_f32 v[14:15], v[192:193], v[14:15]
	v_mfma_f32_32x32x16_bf16 v[32:47], v[104:107], v[52:55], v[32:47]
	v_mfma_f32_32x32x16_bf16 v[16:31], v[108:111], v[200:203], v[16:31]
	v_mfma_f32_32x32x16_bf16 v[0:15], v[112:115], v[144:147], v[0:15]
	global_load_dwordx4 v[92:95], v232, s[34:35] offset:-4096
	v_mfma_f32_32x32x16_bf16 v[0:15], v[116:119], v[148:151], v[0:15]
	global_load_dwordx4 v[96:99], v232, s[34:35]
	v_mfma_f32_32x32x16_bf16 v[0:15], v[120:123], v[152:155], v[0:15]
	global_load_dwordx4 v[100:103], v233, s[34:35] offset:-4096
	v_mfma_f32_32x32x16_bf16 v[0:15], v[124:127], v[156:159], v[0:15]
	global_load_dwordx4 v[104:107], v233, s[34:35]
	ds_read_b128 v[128:131], v246 offset:0
	ds_read_b128 v[132:135], v246 offset:1024
	ds_read_b128 v[136:139], v246 offset:2048
	global_load_dwordx4 v[112:115], v235, s[32:33]
	ds_read_b128 v[140:143], v246 offset:3072
	ds_read_b128 v[196:199], v248 offset:0
	ds_read_b128 v[162:165], v247 offset:0
	ds_read_b128 v[166:169], v247 offset:32
	ds_read_b128 v[170:173], v247 offset:64
	ds_read_b128 v[174:177], v247 offset:96
	global_load_dwordx4 v[116:119], v235, s[32:33] offset:1024
	v_cvt_pk_bf16_f32 v16, v16, v17
	v_cvt_pk_bf16_f32 v18, v18, v19
	v_cvt_pk_bf16_f32 v20, v20, v21
	v_cvt_pk_bf16_f32 v22, v22, v23
	v_cvt_pk_bf16_f32 v24, v24, v25
	v_cvt_pk_bf16_f32 v26, v26, v27
	v_cvt_pk_bf16_f32 v28, v28, v29
	global_load_dwordx4 v[120:123], v235, s[32:33] offset:2048
	v_cvt_pk_bf16_f32 v30, v30, v31
	ds_write2st64_b32 v241, v16, v20 offset0:128 offset1:130
	ds_write2st64_b32 v242, v18, v22 offset0:129 offset1:131
	ds_write2st64_b32 v241, v24, v28 offset0:132 offset1:134
	ds_write2st64_b32 v242, v26, v30 offset0:133 offset1:135
	v_cvt_pk_bf16_f32 v32, v32, v33
	v_cvt_pk_bf16_f32 v34, v34, v35
	global_load_dwordx4 v[124:127], v235, s[32:33] offset:3072
	v_cvt_pk_bf16_f32 v36, v36, v37
	v_cvt_pk_bf16_f32 v38, v38, v39
	v_cvt_pk_bf16_f32 v40, v40, v41
	v_cvt_pk_bf16_f32 v42, v42, v43
	v_cvt_pk_bf16_f32 v44, v44, v45
	v_cvt_pk_bf16_f32 v46, v46, v47
	global_load_dwordx4 v[108:111], v251, s[36:37]
	ds_write2st64_b32 v243, v32, v36 offset0:128 offset1:130
	ds_write2st64_b32 v244, v34, v38 offset0:129 offset1:131
	ds_write2st64_b32 v243, v40, v44 offset0:132 offset1:134
	ds_write2st64_b32 v244, v42, v46 offset0:133 offset1:135
	s_add_u32 s32, s32, s53
	s_addc_u32 s33, s33, s56
	s_add_u32 s34, s34, s53
	s_addc_u32 s35, s35, s56
	s_add_u32 s36, s36, s54
	s_addc_u32 s37, s37, s56
	s_waitcnt lgkmcnt(0)
	s_barrier
	s_add_i32 s30, s30, 2
	s_cmp_lt_u32 s30, 256
	s_cbranch_scc1 .Lscan_loopB
